# gate epilogue: 16 dwordx2 stores per lane and group widened to 8 dwordx4 stores via v_permlane16_swap of neighbouring channel tiles (store tail is issue-bound per instruction)
# speedup vs baseline: 1.0077x; 1.0039x over previous
.LBB0_797:
	s_waitcnt vmcnt(0)
	v_mov_b32_e32 v110, v200
	v_lshl_add_u64 v[132:133], s[42:43], 0, v[94:95]
	v_mov_b32_e32 v134, v202
	v_mov_b32_e32 v135, v203
	v_mov_b32_e32 v136, v204
	v_mov_b32_e32 v137, v205
	v_mov_b32_e32 v138, v206
	v_mov_b32_e32 v139, v207
	v_mov_b32_e32 v140, v208
	v_mov_b32_e32 v141, v209
	v_mov_b32_e32 v142, v210
	v_mov_b32_e32 v143, v211
	v_mov_b32_e32 v144, v212
	v_mov_b32_e32 v145, v213
	v_mov_b32_e32 v146, v214
	v_mov_b32_e32 v147, v215
	v_mov_b32_e32 v148, v216
	v_mov_b32_e32 v149, v217
	s_waitcnt vmcnt(7)
	v_lshlrev_b32_e32 v150, 16, v134
	v_and_b32_e32 v151, 0xffff0000, v134
	v_lshlrev_b32_e32 v134, 16, v135
	v_and_b32_e32 v135, 0xffff0000, v135
	s_waitcnt vmcnt(6)
	v_lshlrev_b32_e32 v152, 16, v136
	v_pk_add_f32 v[42:43], v[42:43], v[110:111] op_sel_hi:[1,0]
	v_pk_add_f32 v[40:41], v[40:41], v[110:111] op_sel_hi:[1,0]
	v_pk_add_f32 v[38:39], v[38:39], v[110:111] op_sel_hi:[1,0]
	v_pk_add_f32 v[36:37], v[36:37], v[110:111] op_sel_hi:[1,0]
	v_and_b32_e32 v153, 0xffff0000, v136
	v_lshlrev_b32_e32 v136, 16, v137
	v_and_b32_e32 v137, 0xffff0000, v137
	v_pk_add_f32 v[46:47], v[46:47], v[110:111] op_sel_hi:[1,0]
	v_pk_add_f32 v[44:45], v[44:45], v[110:111] op_sel_hi:[1,0]
	v_pk_add_f32 v[50:51], v[50:51], v[110:111] op_sel_hi:[1,0]
	v_pk_add_f32 v[48:49], v[48:49], v[110:111] op_sel_hi:[1,0]
	v_pk_add_f32 v[62:63], v[62:63], v[110:111] op_sel_hi:[1,0]
	v_pk_add_f32 v[60:61], v[60:61], v[110:111] op_sel_hi:[1,0]
	v_pk_add_f32 v[58:59], v[58:59], v[110:111] op_sel_hi:[1,0]
	v_pk_add_f32 v[56:57], v[56:57], v[110:111] op_sel_hi:[1,0]
	s_waitcnt vmcnt(5)
	v_lshlrev_b32_e32 v154, 16, v138
	v_and_b32_e32 v155, 0xffff0000, v138
	v_lshlrev_b32_e32 v138, 16, v139
	v_and_b32_e32 v139, 0xffff0000, v139
	s_waitcnt vmcnt(4)
	v_lshlrev_b32_e32 v156, 16, v140
	v_and_b32_e32 v157, 0xffff0000, v140
	v_lshlrev_b32_e32 v140, 16, v141
	v_and_b32_e32 v141, 0xffff0000, v141
	s_waitcnt vmcnt(3)
	v_lshlrev_b32_e32 v158, 16, v142
	v_and_b32_e32 v159, 0xffff0000, v142
	v_lshlrev_b32_e32 v142, 16, v143
	v_and_b32_e32 v143, 0xffff0000, v143
	s_waitcnt vmcnt(2)
	v_lshlrev_b32_e32 v160, 16, v144
	v_and_b32_e32 v161, 0xffff0000, v144
	v_lshlrev_b32_e32 v144, 16, v145
	v_and_b32_e32 v145, 0xffff0000, v145
	v_pk_mul_f32 v[40:41], v[40:41], v[150:151]
	v_pk_mul_f32 v[42:43], v[42:43], v[134:135]
	v_pk_mul_f32 v[36:37], v[36:37], v[152:153]
	v_pk_mul_f32 v[38:39], v[38:39], v[136:137]
	v_pk_mul_f32 v[44:45], v[44:45], v[154:155]
	v_pk_mul_f32 v[46:47], v[46:47], v[138:139]
	v_pk_mul_f32 v[48:49], v[48:49], v[156:157]
	v_pk_mul_f32 v[50:51], v[50:51], v[140:141]
	v_pk_mul_f32 v[60:61], v[60:61], v[158:159]
	v_pk_mul_f32 v[62:63], v[62:63], v[142:143]
	v_pk_mul_f32 v[56:57], v[56:57], v[160:161]
	v_pk_mul_f32 v[58:59], v[58:59], v[144:145]
	v_cvt_pk_bf16_f32 v40, v40, v41
	v_cvt_pk_bf16_f32 v41, v42, v43
	v_cvt_pk_bf16_f32 v42, v36, v37
	v_cvt_pk_bf16_f32 v43, v38, v39
	v_cvt_pk_bf16_f32 v36, v44, v45
	v_cvt_pk_bf16_f32 v37, v46, v47
	v_cvt_pk_bf16_f32 v38, v48, v49
	v_cvt_pk_bf16_f32 v39, v50, v51
	v_cvt_pk_bf16_f32 v44, v60, v61
	v_cvt_pk_bf16_f32 v45, v62, v63
	v_cvt_pk_bf16_f32 v46, v56, v57
	v_cvt_pk_bf16_f32 v47, v58, v59
	v_bfe_u32 v174, v194, 4, 1
	v_mul_u32_u24_e32 v174, 24, v174
	v_mov_b32_e32 v175, 0
	v_lshl_add_u64 v[176:177], v[132:133], 0, v[174:175]
	s_nop 1
	v_permlane16_swap_b32 v40, v42
	v_permlane16_swap_b32 v41, v43
	v_permlane16_swap_b32 v36, v38
	v_permlane16_swap_b32 v37, v39
	v_permlane16_swap_b32 v44, v46
	v_permlane16_swap_b32 v45, v47
	global_store_dwordx4 v[176:177], v[40:43], off offset:-128
	global_store_dwordx4 v[176:177], v[36:39], off offset:-64
	global_store_dwordx4 v[176:177], v[44:47], off
	v_pk_add_f32 v[32:33], v[32:33], v[110:111] op_sel_hi:[1,0]
	s_waitcnt vmcnt(6)
	v_lshlrev_b32_e32 v36, 16, v148
	v_and_b32_e32 v37, 0xffff0000, v148
	v_pk_add_f32 v[54:55], v[54:55], v[110:111] op_sel_hi:[1,0]
	v_pk_add_f32 v[52:53], v[52:53], v[110:111] op_sel_hi:[1,0]
	v_lshlrev_b32_e32 v162, 16, v146
	v_and_b32_e32 v163, 0xffff0000, v146
	v_lshlrev_b32_e32 v146, 16, v147
	v_and_b32_e32 v147, 0xffff0000, v147
	v_pk_add_f32 v[34:35], v[34:35], v[110:111] op_sel_hi:[1,0]
	v_pk_mul_f32 v[32:33], v[32:33], v[36:37]
	v_lshlrev_b32_e32 v36, 16, v149
	v_and_b32_e32 v37, 0xffff0000, v149
	v_pk_mul_f32 v[52:53], v[52:53], v[162:163]
	v_pk_mul_f32 v[54:55], v[54:55], v[146:147]
	v_pk_mul_f32 v[34:35], v[34:35], v[36:37]
	v_cvt_pk_bf16_f32 v48, v52, v53
	v_cvt_pk_bf16_f32 v49, v54, v55
	v_cvt_pk_bf16_f32 v50, v32, v33
	v_cvt_pk_bf16_f32 v51, v34, v35
	s_nop 1
	v_permlane16_swap_b32 v48, v50
	v_permlane16_swap_b32 v49, v51
	global_store_dwordx4 v[176:177], v[48:51], off offset:64
	s_or_b64 exec, exec, s[26:27]
	s_and_saveexec_b64 s[26:27], s[24:25]
	s_cbranch_execz .LBB0_743
	s_branch .LBB0_801

.LBB0_801:
	v_mov_b32_e32 v32, v201
	v_lshl_add_u64 v[34:35], s[42:43], 0, v[108:109]
	v_mov_b32_e32 v36, v218
	v_mov_b32_e32 v37, v219
	v_mov_b32_e32 v38, v220
	v_mov_b32_e32 v39, v221
	v_mov_b32_e32 v40, v222
	v_mov_b32_e32 v41, v223
	v_mov_b32_e32 v42, v224
	v_mov_b32_e32 v43, v225
	v_mov_b32_e32 v44, v226
	v_mov_b32_e32 v45, v227
	v_mov_b32_e32 v46, v228
	v_mov_b32_e32 v47, v229
	v_mov_b32_e32 v48, v230
	v_mov_b32_e32 v49, v231
	v_mov_b32_e32 v50, v232
	v_mov_b32_e32 v51, v233
	v_lshlrev_b32_e32 v52, 16, v36
	v_and_b32_e32 v53, 0xffff0000, v36
	v_lshlrev_b32_e32 v36, 16, v37
	v_and_b32_e32 v37, 0xffff0000, v37
	v_lshlrev_b32_e32 v54, 16, v38
	v_pk_add_f32 v[30:31], v[30:31], v[32:33] op_sel_hi:[1,0]
	v_pk_add_f32 v[28:29], v[28:29], v[32:33] op_sel_hi:[1,0]
	v_pk_add_f32 v[6:7], v[6:7], v[32:33] op_sel_hi:[1,0]
	v_pk_add_f32 v[4:5], v[4:5], v[32:33] op_sel_hi:[1,0]
	v_lshlrev_b32_e32 v110, 16, v48
	v_and_b32_e32 v111, 0xffff0000, v48
	v_lshlrev_b32_e32 v48, 16, v49
	v_and_b32_e32 v49, 0xffff0000, v49
	v_pk_add_f32 v[26:27], v[26:27], v[32:33] op_sel_hi:[1,0]
	v_pk_add_f32 v[24:25], v[24:25], v[32:33] op_sel_hi:[1,0]
	v_pk_add_f32 v[22:23], v[22:23], v[32:33] op_sel_hi:[1,0]
	v_pk_add_f32 v[20:21], v[20:21], v[32:33] op_sel_hi:[1,0]
	v_pk_add_f32 v[18:19], v[18:19], v[32:33] op_sel_hi:[1,0]
	v_pk_add_f32 v[16:17], v[16:17], v[32:33] op_sel_hi:[1,0]
	v_pk_add_f32 v[14:15], v[14:15], v[32:33] op_sel_hi:[1,0]
	v_pk_add_f32 v[12:13], v[12:13], v[32:33] op_sel_hi:[1,0]
	v_pk_add_f32 v[10:11], v[10:11], v[32:33] op_sel_hi:[1,0]
	v_pk_add_f32 v[8:9], v[8:9], v[32:33] op_sel_hi:[1,0]
	v_and_b32_e32 v55, 0xffff0000, v38
	v_lshlrev_b32_e32 v38, 16, v39
	v_and_b32_e32 v39, 0xffff0000, v39
	v_lshlrev_b32_e32 v56, 16, v40
	v_and_b32_e32 v57, 0xffff0000, v40
	v_lshlrev_b32_e32 v40, 16, v41
	v_and_b32_e32 v41, 0xffff0000, v41
	v_lshlrev_b32_e32 v58, 16, v42
	v_and_b32_e32 v59, 0xffff0000, v42
	v_lshlrev_b32_e32 v42, 16, v43
	v_and_b32_e32 v43, 0xffff0000, v43
	v_lshlrev_b32_e32 v60, 16, v44
	v_and_b32_e32 v61, 0xffff0000, v44
	v_lshlrev_b32_e32 v44, 16, v45
	v_and_b32_e32 v45, 0xffff0000, v45
	v_lshlrev_b32_e32 v62, 16, v46
	v_and_b32_e32 v63, 0xffff0000, v46
	v_lshlrev_b32_e32 v46, 16, v47
	v_and_b32_e32 v47, 0xffff0000, v47
	v_pk_mul_f32 v[28:29], v[28:29], v[52:53]
	v_pk_mul_f32 v[30:31], v[30:31], v[36:37]
	v_pk_mul_f32 v[4:5], v[4:5], v[110:111]
	v_pk_mul_f32 v[6:7], v[6:7], v[48:49]
	v_pk_mul_f32 v[24:25], v[24:25], v[54:55]
	v_pk_mul_f32 v[26:27], v[26:27], v[38:39]
	v_pk_mul_f32 v[20:21], v[20:21], v[56:57]
	v_pk_mul_f32 v[22:23], v[22:23], v[40:41]
	v_pk_mul_f32 v[16:17], v[16:17], v[58:59]
	v_pk_mul_f32 v[18:19], v[18:19], v[42:43]
	v_pk_mul_f32 v[12:13], v[12:13], v[60:61]
	v_pk_mul_f32 v[14:15], v[14:15], v[44:45]
	v_pk_mul_f32 v[8:9], v[8:9], v[62:63]
	v_pk_mul_f32 v[10:11], v[10:11], v[46:47]
	v_cvt_pk_bf16_f32 v28, v28, v29
	v_cvt_pk_bf16_f32 v29, v30, v31
	v_cvt_pk_bf16_f32 v4, v4, v5
	v_cvt_pk_bf16_f32 v5, v6, v7
	v_cvt_pk_bf16_f32 v30, v24, v25
	v_cvt_pk_bf16_f32 v31, v26, v27
	v_cvt_pk_bf16_f32 v20, v20, v21
	v_cvt_pk_bf16_f32 v21, v22, v23
	v_cvt_pk_bf16_f32 v22, v16, v17
	v_cvt_pk_bf16_f32 v23, v18, v19
	v_cvt_pk_bf16_f32 v12, v12, v13
	v_cvt_pk_bf16_f32 v13, v14, v15
	v_cvt_pk_bf16_f32 v14, v8, v9
	v_cvt_pk_bf16_f32 v15, v10, v11
	v_bfe_u32 v174, v194, 4, 1
	v_mul_u32_u24_e32 v174, 24, v174
	v_mov_b32_e32 v175, 0
	v_lshl_add_u64 v[178:179], v[34:35], 0, v[174:175]
	s_nop 1
	v_permlane16_swap_b32 v28, v30
	v_permlane16_swap_b32 v29, v31
	v_permlane16_swap_b32 v20, v22
	v_permlane16_swap_b32 v21, v23
	v_permlane16_swap_b32 v12, v14
	v_permlane16_swap_b32 v13, v15
	global_store_dwordx4 v[178:179], v[28:31], off offset:-128
	global_store_dwordx4 v[178:179], v[20:23], off offset:-64
	global_store_dwordx4 v[178:179], v[12:15], off
	v_pk_add_f32 v[0:1], v[0:1], v[32:33] op_sel_hi:[1,0]
	v_lshlrev_b32_e32 v172, 16, v50
	v_and_b32_e32 v173, 0xffff0000, v50
	v_pk_add_f32 v[2:3], v[2:3], v[32:33] op_sel_hi:[1,0]
	v_pk_mul_f32 v[0:1], v[0:1], v[172:173]
	v_lshlrev_b32_e32 v172, 16, v51
	v_and_b32_e32 v173, 0xffff0000, v51
	v_pk_mul_f32 v[2:3], v[2:3], v[172:173]
	v_cvt_pk_bf16_f32 v6, v0, v1
	v_cvt_pk_bf16_f32 v7, v2, v3
	s_nop 1
	v_permlane16_swap_b32 v4, v6
	v_permlane16_swap_b32 v5, v7
	global_store_dwordx4 v[178:179], v[4:7], off offset:64
	s_branch .LBB0_743
